# speedup vs baseline: 1.0158x; 1.0158x over previous
; #define LAS __attribute__((address_space(3)))
; __device__ __forceinline__ unsigned pk2(float lo, float hi) { unsigned r; asm volatile("v_cvt_pk_bf16_f32 %0, %1, %2" : "=v"(r) : "v"(lo), "v"(hi)); return r; }
; __device__ __forceinline__ void p0_transpose_item(const float* W, int K, int N, const float* gain, const float* gain2  , bf16_t* WT, LAS unsigned* scr, int item, int lane) {
;     ...
;     for (int j = 0; j < 8; ++j) {
;         float g0 = 1.f, g1 = 1.f; if (gain) { g0 = gain[k0 + 8 * j + 2 * kq]; g1 = gain[k0 + 8 * j + 2 * kq + 1]; }
; #pragma unroll
;         for (int i = 0; i < 4; ++i) scr[(4 * n4 + i) * 32 + (((j ^ (n4 & 7)) << 2) | kq)] = pk2(r0[j][i] * g0, r1[j][i] * g1);
;     }
;     asm volatile("s_waitcnt lgkmcnt(0)" ::: "memory");
; #pragma unroll
;     for (int it = 0; it < 8; ++it) {
;         const int n = (lane >> 3) + 8 * it, c = lane & 7;
;         const u32x4 v = *(const LAS u32x4*)(scr + n * 32 + ((c ^ ((n >> 2) & 7)) << 2));
;         *(u32x4*)(WT + (size_t)(n0 + n) * K + k0 + 8 * c) = v;
;     }
.Lmy_w116:
	s_waitcnt vmcnt(0)
	v_mul_f32_e32 v26, v26, v42
	v_mul_f32_e32 v30, v30, v43
	v_cvt_pk_bf16_f32 v26, v26, v30
	v_add_u32_e32 v30, v117, v110
	ds_write_b32 v30, v26
	v_mul_f32_e32 v26, v27, v42
	v_mul_f32_e32 v27, v31, v43
	v_cvt_pk_bf16_f32 v26, v26, v27
	ds_write_b32 v30, v26 offset:128
	v_mul_f32_e32 v26, v28, v42
	v_mul_f32_e32 v27, v32, v43
	v_cvt_pk_bf16_f32 v26, v26, v27
	ds_write_b32 v30, v26 offset:256
	v_mul_f32_e32 v26, v29, v42
	v_mul_f32_e32 v27, v33, v43
	v_cvt_pk_bf16_f32 v26, v26, v27
	ds_write_b32 v30, v26 offset:384
	v_ashrrev_i32_e32 v105, 31, v104
	s_waitcnt lgkmcnt(0)
	v_lshl_add_u64 v[26:27], v[104:105], 1, v[98:99]
	v_lshlrev_b32_e32 v28, 1, v94
	v_mov_b32_e32 v29, v93
	v_lshl_add_u64 v[34:35], v[26:27], 0, v[28:29]
	ds_read_b128 v[26:29], v119
	v_or_b32_e32 v30, v102, v118
	v_ashrrev_i32_e32 v31, 31, v30
	v_lshlrev_b64 v[30:31], 12, v[30:31]
	v_lshl_add_u64 v[36:37], v[34:35], 0, v[30:31]
	ds_read_b128 v[30:33], v121
	s_waitcnt lgkmcnt(1)
	global_store_dwordx4 v[36:37], v[26:29], off sc0 sc1
	s_nop 1
	v_or_b32_e32 v26, v102, v120
	v_ashrrev_i32_e32 v27, 31, v26
	v_lshlrev_b64 v[26:27], 12, v[26:27]
	v_lshl_add_u64 v[26:27], v[34:35], 0, v[26:27]
	s_waitcnt lgkmcnt(0)
	global_store_dwordx4 v[26:27], v[30:33], off sc0 sc1
	ds_read_b128 v[26:29], v123
	s_nop 0
	v_or_b32_e32 v30, v102, v122
	v_ashrrev_i32_e32 v31, 31, v30
	v_lshlrev_b64 v[30:31], 12, v[30:31]
	v_lshl_add_u64 v[36:37], v[34:35], 0, v[30:31]
	ds_read_b128 v[30:33], v125
	s_waitcnt lgkmcnt(1)
	global_store_dwordx4 v[36:37], v[26:29], off sc0 sc1
	s_nop 1
	v_or_b32_e32 v26, v102, v124
	v_ashrrev_i32_e32 v27, 31, v26
	v_lshlrev_b64 v[26:27], 12, v[26:27]
	v_lshl_add_u64 v[26:27], v[34:35], 0, v[26:27]
	s_waitcnt lgkmcnt(0)
	global_store_dwordx4 v[26:27], v[30:33], off sc0 sc1
	ds_read_b128 v[26:29], v127
	s_nop 0
	v_or_b32_e32 v30, v102, v126
	v_ashrrev_i32_e32 v31, 31, v30
	v_lshlrev_b64 v[30:31], 12, v[30:31]
	v_lshl_add_u64 v[36:37], v[34:35], 0, v[30:31]
	ds_read_b128 v[30:33], v129
	s_waitcnt lgkmcnt(1)
	global_store_dwordx4 v[36:37], v[26:29], off sc0 sc1
	s_nop 1
	v_or_b32_e32 v26, v102, v128
	v_ashrrev_i32_e32 v27, 31, v26
	v_lshlrev_b64 v[26:27], 12, v[26:27]
	v_lshl_add_u64 v[26:27], v[34:35], 0, v[26:27]
	s_waitcnt lgkmcnt(0)
	global_store_dwordx4 v[26:27], v[30:33], off sc0 sc1
	ds_read_b128 v[26:29], v131
	s_nop 0
	v_or_b32_e32 v30, v102, v130
	v_ashrrev_i32_e32 v31, 31, v30
	v_lshlrev_b64 v[30:31], 12, v[30:31]
	v_lshl_add_u64 v[36:37], v[34:35], 0, v[30:31]
	ds_read_b128 v[30:33], v133
	s_waitcnt lgkmcnt(1)
	global_store_dwordx4 v[36:37], v[26:29], off sc0 sc1
	s_nop 1
	v_or_b32_e32 v26, v102, v132
	v_ashrrev_i32_e32 v27, 31, v26
	v_lshlrev_b64 v[26:27], 12, v[26:27]
	v_lshl_add_u64 v[26:27], v[34:35], 0, v[26:27]
	s_waitcnt lgkmcnt(0)
	global_store_dwordx4 v[26:27], v[30:33], off sc0 sc1
	s_waitcnt lgkmcnt(0)

; #define LAS __attribute__((address_space(3)))
; __device__ __forceinline__ unsigned pk2(float lo, float hi) { unsigned r; asm volatile("v_cvt_pk_bf16_f32 %0, %1, %2" : "=v"(r) : "v"(lo), "v"(hi)); return r; }
; __device__ __forceinline__ void p0_transpose_item(const float* W, int K, int N, const float* gain, const float* gain2  , bf16_t* WT, LAS unsigned* scr, int item, int lane) {
;     const int nblk = N / 64, kb = item / nblk, nb = item % nblk, k0 = 64 * kb, n0 = 64 * nb;
;     if (gain2 && k0 >= 1024) gain = gain2 - 1024;
;     const int n4 = lane & 15, kq = lane >> 4;
;     f32x4 r0[8], r1[8];
;     const float* src = W + (size_t)(k0 + 2 * kq) * N + n0 + 4 * n4;
; #pragma unroll
;     for (int j = 0; j < 8; ++j) { r0[j] = __builtin_nontemporal_load((const f32x4*)(src + (size_t)(8 * j) * N)); r1[j] = __builtin_nontemporal_load((const f32x4*)(src + (size_t)(8 * j + 1) * N)); }
;     ...
;     for (int j = 0; j < 8; ++j) {
;         float g0 = 1.f, g1 = 1.f; if (gain) { g0 = gain[k0 + 8 * j + 2 * kq]; g1 = gain[k0 + 8 * j + 2 * kq + 1]; }
; #pragma unroll
;         for (int i = 0; i < 4; ++i) scr[(4 * n4 + i) * 32 + (((j ^ (n4 & 7)) << 2) | kq)] = pk2(r0[j][i] * g0, r1[j][i] * g1);
;     }
;     asm volatile("s_waitcnt lgkmcnt(0)" ::: "memory");
; #pragma unroll
;     for (int it = 0; it < 8; ++it) {
;         const int n = (lane >> 3) + 8 * it, c = lane & 7;
;         const u32x4 v = *(const LAS u32x4*)(scr + n * 32 + ((c ^ ((n >> 2) & 7)) << 2));
;         *(u32x4*)(WT + (size_t)(n0 + n) * K + k0 + 8 * c) = v;
;     }
.Lmy_w138:
	s_or_b64 exec, exec, s[34:35]
	s_waitcnt vmcnt(0)
	v_mul_f32_e32 v26, v26, v42
	v_mul_f32_e32 v30, v30, v43
	v_cvt_pk_bf16_f32 v26, v26, v30
	v_add_u32_e32 v30, v117, v110
	ds_write_b32 v30, v26
	v_mul_f32_e32 v26, v27, v42
	v_mul_f32_e32 v27, v31, v43
	v_cvt_pk_bf16_f32 v26, v26, v27
	ds_write_b32 v30, v26 offset:128
	v_mul_f32_e32 v26, v28, v42
	v_mul_f32_e32 v27, v32, v43
	v_cvt_pk_bf16_f32 v26, v26, v27
	ds_write_b32 v30, v26 offset:256
	v_mul_f32_e32 v26, v29, v42
	v_mul_f32_e32 v27, v33, v43
	v_cvt_pk_bf16_f32 v26, v26, v27
	ds_write_b32 v30, v26 offset:384
	v_lshlrev_b32_e32 v26, 1, v109
	v_mov_b32_e32 v27, v93
	v_lshl_add_u64 v[26:27], v[98:99], 0, v[26:27]
	v_lshlrev_b32_e32 v28, 1, v94
	v_mov_b32_e32 v29, v93
	s_waitcnt lgkmcnt(0)
	v_lshl_add_u64 v[26:27], v[26:27], 0, v[28:29]
	v_lshl_add_u64 v[34:35], v[26:27], 0, s[18:19]
	ds_read_b128 v[26:29], v119
	v_or_b32_e32 v30, v108, v118
	v_lshlrev_b32_e32 v30, 12, v30
	v_mov_b32_e32 v31, v93
	v_lshl_add_u64 v[36:37], v[34:35], 0, v[30:31]
	ds_read_b128 v[30:33], v121
	s_waitcnt lgkmcnt(1)
	global_store_dwordx4 v[36:37], v[26:29], off sc0 sc1
	s_nop 1
	v_or_b32_e32 v26, v108, v120
	v_lshlrev_b32_e32 v26, 12, v26
	v_mov_b32_e32 v27, v93
	v_lshl_add_u64 v[26:27], v[34:35], 0, v[26:27]
	s_waitcnt lgkmcnt(0)
	global_store_dwordx4 v[26:27], v[30:33], off sc0 sc1
	ds_read_b128 v[26:29], v123
	s_nop 0
	v_or_b32_e32 v30, v108, v122
	v_lshlrev_b32_e32 v30, 12, v30
	v_mov_b32_e32 v31, v93
	v_lshl_add_u64 v[36:37], v[34:35], 0, v[30:31]
	ds_read_b128 v[30:33], v125
	s_waitcnt lgkmcnt(1)
	global_store_dwordx4 v[36:37], v[26:29], off sc0 sc1
	s_nop 1
	v_or_b32_e32 v26, v108, v124
	v_lshlrev_b32_e32 v26, 12, v26
	v_mov_b32_e32 v27, v93
	v_lshl_add_u64 v[26:27], v[34:35], 0, v[26:27]
	s_waitcnt lgkmcnt(0)
	global_store_dwordx4 v[26:27], v[30:33], off sc0 sc1
	ds_read_b128 v[26:29], v127
	s_nop 0
	v_or_b32_e32 v30, v108, v126
	v_lshlrev_b32_e32 v30, 12, v30
	v_mov_b32_e32 v31, v93
	v_lshl_add_u64 v[36:37], v[34:35], 0, v[30:31]
	ds_read_b128 v[30:33], v129
	s_waitcnt lgkmcnt(1)
	global_store_dwordx4 v[36:37], v[26:29], off sc0 sc1
	s_nop 1
	v_or_b32_e32 v26, v108, v128
	v_lshlrev_b32_e32 v26, 12, v26
	v_mov_b32_e32 v27, v93
	v_lshl_add_u64 v[26:27], v[34:35], 0, v[26:27]
	s_waitcnt lgkmcnt(0)
	global_store_dwordx4 v[26:27], v[30:33], off sc0 sc1
	ds_read_b128 v[26:29], v131
	s_nop 0
	v_or_b32_e32 v30, v108, v130
	v_lshlrev_b32_e32 v30, 12, v30
	v_mov_b32_e32 v31, v93
	v_lshl_add_u64 v[36:37], v[34:35], 0, v[30:31]
	ds_read_b128 v[30:33], v133
	s_waitcnt lgkmcnt(1)
	global_store_dwordx4 v[36:37], v[26:29], off sc0 sc1
	s_nop 1
	v_or_b32_e32 v26, v108, v132
	v_lshlrev_b32_e32 v26, 12, v26
	v_mov_b32_e32 v27, v93
	v_lshl_add_u64 v[26:27], v[34:35], 0, v[26:27]
	s_waitcnt lgkmcnt(0)
	global_store_dwordx4 v[26:27], v[30:33], off sc0 sc1
	s_waitcnt lgkmcnt(0)
.Lmy_w139:
	s_andn2_saveexec_b64 s[30:31], s[30:31]
	s_cbranch_execz .Lmy_w141
	v_lshlrev_b32_e32 v26, 2, v27
	v_sub_u32_e32 v26, v135, v26
	v_lshlrev_b64 v[28:29], 22, v[100:101]
	v_and_b32_e32 v100, 0x3c0, v26
	v_lshlrev_b32_e32 v26, 6, v27
	v_sub_u32_e32 v26, v134, v26
	v_lshl_add_u64 v[28:29], s[62:63], 0, v[28:29]
	v_and_b32_e32 v101, 0x3c0, v26
	v_lshl_or_b32 v26, v100, 12, v136
	v_mov_b32_e32 v27, v93
	v_lshl_add_u64 v[26:27], v[28:29], 0, v[26:27]
	v_lshlrev_b32_e32 v28, 2, v101
	v_mov_b32_e32 v29, v93
	v_lshl_add_u64 v[26:27], v[26:27], 0, v[28:29]
	v_lshl_add_u64 v[82:83], v[26:27], 0, v[92:93]
	s_movk_i32 s34, 0x1000
	v_add_co_u32_e32 v30, vcc, s34, v82
	s_mov_b32 s34, 0x9000
	s_nop 0
	v_addc_co_u32_e32 v31, vcc, 0, v83, vcc
	global_load_dwordx4 v[26:29], v[82:83], off nt
	s_nop 0
	global_load_dwordx4 v[30:33], v[30:31], off nt
	v_add_co_u32_e32 v38, vcc, s34, v82
	s_mov_b32 s34, 0x11000
	s_nop 0
	v_addc_co_u32_e32 v39, vcc, 0, v83, vcc
	global_load_dwordx4 v[34:37], v[38:39], off offset:-4096 nt
	s_nop 0
	global_load_dwordx4 v[38:41], v[38:39], off nt
	v_add_co_u32_e32 v46, vcc, s34, v82
	s_mov_b32 s34, 0x19000
	s_nop 0
	v_addc_co_u32_e32 v47, vcc, 0, v83, vcc
	global_load_dwordx4 v[42:45], v[46:47], off offset:-4096 nt
	s_nop 0
	global_load_dwordx4 v[46:49], v[46:47], off nt
	v_add_co_u32_e32 v54, vcc, s34, v82
	s_mov_b32 s34, 0x21000
	s_nop 0
	v_addc_co_u32_e32 v55, vcc, 0, v83, vcc
	global_load_dwordx4 v[50:53], v[54:55], off offset:-4096 nt
	s_waitcnt lgkmcnt(0)
	global_load_dwordx4 v[54:57], v[54:55], off nt
	v_add_co_u32_e32 v62, vcc, s34, v82
	s_mov_b32 s34, 0x29000
	s_nop 0
	v_addc_co_u32_e32 v63, vcc, 0, v83, vcc
	global_load_dwordx4 v[58:61], v[62:63], off offset:-4096 nt
	s_nop 0
	global_load_dwordx4 v[62:65], v[62:63], off nt
	v_add_co_u32_e32 v70, vcc, s34, v82
	s_mov_b32 s34, 0x31000
	s_nop 0
	v_addc_co_u32_e32 v71, vcc, 0, v83, vcc
	global_load_dwordx4 v[66:69], v[70:71], off offset:-4096 nt
	s_nop 0
	global_load_dwordx4 v[70:73], v[70:71], off nt
	v_add_co_u32_e32 v78, vcc, s34, v82
	v_add_u32_e32 v102, v95, v110
	s_nop 0
	v_addc_co_u32_e32 v79, vcc, 0, v83, vcc
	global_load_dwordx4 v[74:77], v[78:79], off offset:-4096 nt
	s_nop 0
	global_load_dwordx4 v[78:81], v[78:79], off nt
	v_add_co_u32_e32 v86, vcc, s85, v82
	v_add_u32_e32 v103, v111, v110
	s_nop 0
	v_addc_co_u32_e32 v87, vcc, 0, v83, vcc
	global_load_dwordx4 v[82:85], v[86:87], off offset:-4096 nt
	s_nop 0
	global_load_dwordx4 v[86:89], v[86:87], off nt
	v_add_u32_e32 v104, v112, v110
	v_add_u32_e32 v105, v113, v110
	v_add_u32_e32 v106, v114, v110
	s_waitcnt vmcnt(14)
; #define LAS __attribute__((address_space(3)))
; __device__ __forceinline__ unsigned pk2(float lo, float hi) { unsigned r; asm volatile("v_cvt_pk_bf16_f32 %0, %1, %2" : "=v"(r) : "v"(lo), "v"(hi)); return r; }
; __device__ __forceinline__ void p0_transpose_item(const float* W, int K, int N, const float* gain, const float* gain2  , bf16_t* WT, LAS unsigned* scr, int item, int lane) {
;     ...
;     for (int j = 0; j < 8; ++j) {
;         float g0 = 1.f, g1 = 1.f; if (gain) { g0 = gain[k0 + 8 * j + 2 * kq]; g1 = gain[k0 + 8 * j + 2 * kq + 1]; }
; #pragma unroll
;         for (int i = 0; i < 4; ++i) scr[(4 * n4 + i) * 32 + (((j ^ (n4 & 7)) << 2) | kq)] = pk2(r0[j][i] * g0, r1[j][i] * g1);
;     }
;     asm volatile("s_waitcnt lgkmcnt(0)" ::: "memory");
; #pragma unroll
;     for (int it = 0; it < 8; ++it) {
;         const int n = (lane >> 3) + 8 * it, c = lane & 7;
;         const u32x4 v = *(const LAS u32x4*)(scr + n * 32 + ((c ^ ((n >> 2) & 7)) << 2));
;         *(u32x4*)(WT + (size_t)(n0 + n) * K + k0 + 8 * c) = v;
;     }
	v_cvt_pk_bf16_f32 v26, v26, v30
	ds_write_b32 v102, v26
	v_cvt_pk_bf16_f32 v26, v27, v31
	ds_write_b32 v102, v26 offset:128
	v_cvt_pk_bf16_f32 v26, v28, v32
	ds_write_b32 v102, v26 offset:256
	v_cvt_pk_bf16_f32 v26, v29, v33
	ds_write_b32 v102, v26 offset:384
	s_waitcnt vmcnt(12)
	v_cvt_pk_bf16_f32 v26, v34, v38
	ds_write_b32 v103, v26
	v_cvt_pk_bf16_f32 v26, v35, v39
	ds_write_b32 v103, v26 offset:128
	v_cvt_pk_bf16_f32 v26, v36, v40
	ds_write_b32 v103, v26 offset:256
	v_cvt_pk_bf16_f32 v26, v37, v41
	ds_write_b32 v103, v26 offset:384
	s_waitcnt vmcnt(10)
	v_cvt_pk_bf16_f32 v26, v42, v46
	ds_write_b32 v104, v26
	v_cvt_pk_bf16_f32 v26, v43, v47
	ds_write_b32 v104, v26 offset:128
	v_cvt_pk_bf16_f32 v26, v44, v48
	ds_write_b32 v104, v26 offset:256
	v_cvt_pk_bf16_f32 v26, v45, v49
	ds_write_b32 v104, v26 offset:384
	s_waitcnt vmcnt(8)
	v_cvt_pk_bf16_f32 v26, v50, v54
	ds_write_b32 v105, v26
	v_cvt_pk_bf16_f32 v26, v51, v55
	ds_write_b32 v105, v26 offset:128
	v_cvt_pk_bf16_f32 v26, v52, v56
	ds_write_b32 v105, v26 offset:256
	v_cvt_pk_bf16_f32 v26, v53, v57
	ds_write_b32 v105, v26 offset:384
	s_waitcnt vmcnt(6)
	v_cvt_pk_bf16_f32 v26, v58, v62
	ds_write_b32 v106, v26
	v_cvt_pk_bf16_f32 v26, v59, v63
	ds_write_b32 v106, v26 offset:128
	v_cvt_pk_bf16_f32 v26, v60, v64
	ds_write_b32 v106, v26 offset:256
	v_cvt_pk_bf16_f32 v26, v61, v65
	ds_write_b32 v106, v26 offset:384
	s_waitcnt vmcnt(4)
	v_cvt_pk_bf16_f32 v26, v66, v70
	v_add_u32_e32 v27, v115, v110
	ds_write_b32 v27, v26
	v_cvt_pk_bf16_f32 v26, v67, v71
	ds_write_b32 v27, v26 offset:128
	v_cvt_pk_bf16_f32 v26, v68, v72
	ds_write_b32 v27, v26 offset:256
	v_cvt_pk_bf16_f32 v26, v69, v73
	ds_write_b32 v27, v26 offset:384
	s_waitcnt vmcnt(2)
	v_cvt_pk_bf16_f32 v26, v74, v78
	v_add_u32_e32 v27, v116, v110
	ds_write_b32 v27, v26
	v_cvt_pk_bf16_f32 v26, v75, v79
	ds_write_b32 v27, v26 offset:128
	v_cvt_pk_bf16_f32 v26, v76, v80
	ds_write_b32 v27, v26 offset:256
	v_cvt_pk_bf16_f32 v26, v77, v81
	ds_write_b32 v27, v26 offset:384
	s_waitcnt vmcnt(0)
	v_cvt_pk_bf16_f32 v26, v82, v86
	v_add_u32_e32 v27, v117, v110
	ds_write_b32 v27, v26
	v_cvt_pk_bf16_f32 v26, v83, v87
	ds_write_b32 v27, v26 offset:128
	v_cvt_pk_bf16_f32 v26, v84, v88
	ds_write_b32 v27, v26 offset:256
	v_cvt_pk_bf16_f32 v26, v85, v89
	ds_write_b32 v27, v26 offset:384
	v_lshlrev_b32_e32 v26, 1, v100
	v_mov_b32_e32 v27, v93
	v_lshl_add_u64 v[26:27], v[98:99], 0, v[26:27]
	v_lshlrev_b32_e32 v28, 1, v94
	v_mov_b32_e32 v29, v93
	s_waitcnt lgkmcnt(0)
	v_lshl_add_u64 v[26:27], v[26:27], 0, v[28:29]
	v_lshl_add_u64 v[34:35], v[26:27], 0, s[20:21]
	ds_read_b128 v[26:29], v119
	v_or_b32_e32 v30, v101, v118
	v_lshlrev_b32_e32 v30, 11, v30
	v_mov_b32_e32 v31, v93
	v_lshl_add_u64 v[36:37], v[34:35], 0, v[30:31]
	ds_read_b128 v[30:33], v121
	s_waitcnt lgkmcnt(1)
	global_store_dwordx4 v[36:37], v[26:29], off sc0 sc1
	s_nop 1
	v_or_b32_e32 v26, v101, v120
	v_lshlrev_b32_e32 v26, 11, v26
	v_mov_b32_e32 v27, v93
	v_lshl_add_u64 v[26:27], v[34:35], 0, v[26:27]
	s_waitcnt lgkmcnt(0)
	global_store_dwordx4 v[26:27], v[30:33], off sc0 sc1
	ds_read_b128 v[26:29], v123
	s_nop 0
	v_or_b32_e32 v30, v101, v122
	v_lshlrev_b32_e32 v30, 11, v30
	v_mov_b32_e32 v31, v93
	v_lshl_add_u64 v[36:37], v[34:35], 0, v[30:31]
	ds_read_b128 v[30:33], v125
	s_waitcnt lgkmcnt(1)
	global_store_dwordx4 v[36:37], v[26:29], off sc0 sc1
	s_nop 1
	v_or_b32_e32 v26, v101, v124
	v_lshlrev_b32_e32 v26, 11, v26
	v_mov_b32_e32 v27, v93
	v_lshl_add_u64 v[26:27], v[34:35], 0, v[26:27]
	s_waitcnt lgkmcnt(0)
	global_store_dwordx4 v[26:27], v[30:33], off sc0 sc1
	ds_read_b128 v[26:29], v127
	s_nop 0
	v_or_b32_e32 v30, v101, v126
	v_lshlrev_b32_e32 v30, 11, v30
	v_mov_b32_e32 v31, v93
	v_lshl_add_u64 v[36:37], v[34:35], 0, v[30:31]
	ds_read_b128 v[30:33], v129
	s_waitcnt lgkmcnt(1)
	global_store_dwordx4 v[36:37], v[26:29], off sc0 sc1
	s_nop 1
	v_or_b32_e32 v26, v101, v128
	v_lshlrev_b32_e32 v26, 11, v26
	v_mov_b32_e32 v27, v93
	v_lshl_add_u64 v[26:27], v[34:35], 0, v[26:27]
	s_waitcnt lgkmcnt(0)
	global_store_dwordx4 v[26:27], v[30:33], off sc0 sc1
	ds_read_b128 v[26:29], v131
	s_nop 0
	v_or_b32_e32 v30, v101, v130
	v_lshlrev_b32_e32 v30, 11, v30
	v_mov_b32_e32 v31, v93
	v_lshl_add_u64 v[36:37], v[34:35], 0, v[30:31]
	ds_read_b128 v[30:33], v133
	s_waitcnt lgkmcnt(1)
	global_store_dwordx4 v[36:37], v[26:29], off sc0 sc1
	s_nop 1
	v_or_b32_e32 v26, v101, v132
	v_lshlrev_b32_e32 v26, 11, v26
	v_mov_b32_e32 v27, v93
	v_lshl_add_u64 v[26:27], v[34:35], 0, v[26:27]
	s_waitcnt lgkmcnt(0)
	global_store_dwordx4 v[26:27], v[30:33], off sc0 sc1
	s_waitcnt lgkmcnt(0)

; __device__ __forceinline__ unsigned pk2(float lo, float hi) { unsigned r; asm volatile("v_cvt_pk_bf16_f32 %0, %1, %2" : "=v"(r) : "v"(lo), "v"(hi)); return r; }
; __device__ __forceinline__ void p0_transpose_item(const float* W, int K, int N, const float* gain, const float* gain2  , bf16_t* WT, LAS unsigned* scr, int item, int lane) {
;     const int nblk = N / 64, kb = item / nblk, nb = item % nblk, k0 = 64 * kb, n0 = 64 * nb;
;     if (gain2 && k0 >= 1024) gain = gain2 - 1024;
;     const int n4 = lane & 15, kq = lane >> 4;
;     f32x4 r0[8], r1[8];
;     const float* src = W + (size_t)(k0 + 2 * kq) * N + n0 + 4 * n4;
; #pragma unroll
;     for (int j = 0; j < 8; ++j) { r0[j] = __builtin_nontemporal_load((const f32x4*)(src + (size_t)(8 * j) * N)); r1[j] = __builtin_nontemporal_load((const f32x4*)(src + (size_t)(8 * j + 1) * N)); }
; #pragma unroll
;     for (int j = 0; j < 8; ++j) {
;         float g0 = 1.f, g1 = 1.f; if (gain) { g0 = gain[k0 + 8 * j + 2 * kq]; g1 = gain[k0 + 8 * j + 2 * kq + 1]; }
; #pragma unroll
;         for (int i = 0; i < 4; ++i) scr[(4 * n4 + i) * 32 + (((j ^ (n4 & 7)) << 2) | kq)] = pk2(r0[j][i] * g0, r1[j][i] * g1);
.Lmy_w142:
	s_andn2_saveexec_b64 s[28:29], s[28:29]
	s_cbranch_execz .Lmy_w144
	v_add_u32_e32 v26, 0xeb00, v26
	v_lshlrev_b64 v[28:29], 26, v[100:101]
	v_readlane_b32 s40, v253, 18
	v_bfe_u32 v100, v26, 5, 11
	v_lshlrev_b32_e32 v26, 6, v27
	v_readlane_b32 s52, v253, 30
	v_readlane_b32 s53, v253, 31
	v_sub_u32_e32 v26, v134, v26
	v_and_b32_e32 v101, 0x7c0, v26
	v_lshl_add_u64 v[28:29], s[52:53], 0, v[28:29]
	v_lshl_or_b32 v26, v100, 19, v137
	v_mov_b32_e32 v27, v93
	v_lshl_add_u64 v[26:27], v[28:29], 0, v[26:27]
	v_lshlrev_b32_e32 v28, 2, v101
	v_mov_b32_e32 v29, v93
	v_lshl_add_u64 v[26:27], v[26:27], 0, v[28:29]
	v_lshl_add_u64 v[82:83], v[26:27], 0, v[92:93]
	v_add_co_u32_e32 v30, vcc, s37, v82
	s_mov_b32 s30, 0x72000
	s_nop 0
	v_addc_co_u32_e32 v31, vcc, 0, v83, vcc
	global_load_dwordx4 v[26:29], v[82:83], off nt
	s_nop 0
	global_load_dwordx4 v[30:33], v[30:31], off nt
	v_add_co_u32_e32 v34, vcc, s38, v82
	v_readlane_b32 s41, v253, 19
	s_nop 0
	v_addc_co_u32_e32 v35, vcc, 0, v83, vcc
	v_add_co_u32_e32 v38, vcc, s39, v82
	v_readlane_b32 s42, v253, 20
	s_nop 0
	v_addc_co_u32_e32 v39, vcc, 0, v83, vcc
	global_load_dwordx4 v[34:37], v[34:35], off nt
	s_nop 0
	global_load_dwordx4 v[38:41], v[38:39], off nt
	v_add_co_u32_e32 v42, vcc, s2, v82
	v_readlane_b32 s43, v253, 21
	s_nop 0
	v_addc_co_u32_e32 v43, vcc, 0, v83, vcc
	v_add_co_u32_e32 v46, vcc, s3, v82
	v_readlane_b32 s44, v253, 22
	s_nop 0
	v_addc_co_u32_e32 v47, vcc, 0, v83, vcc
	global_load_dwordx4 v[42:45], v[42:43], off nt
	s_nop 0
	global_load_dwordx4 v[46:49], v[46:47], off nt
	v_add_co_u32_e32 v50, vcc, s76, v82
	v_readlane_b32 s45, v253, 23
	s_nop 0
	v_addc_co_u32_e32 v51, vcc, 0, v83, vcc
	v_add_co_u32_e32 v54, vcc, s77, v82
	v_readlane_b32 s46, v253, 24
	s_nop 0
	v_addc_co_u32_e32 v55, vcc, 0, v83, vcc
	global_load_dwordx4 v[50:53], v[50:51], off nt
	s_waitcnt lgkmcnt(0)
	global_load_dwordx4 v[54:57], v[54:55], off nt
	v_add_co_u32_e32 v58, vcc, s78, v82
	v_readlane_b32 s47, v253, 25
	s_nop 0
	v_addc_co_u32_e32 v59, vcc, 0, v83, vcc
	v_add_co_u32_e32 v62, vcc, s79, v82
	v_readlane_b32 s48, v253, 26
	s_nop 0
	v_addc_co_u32_e32 v63, vcc, 0, v83, vcc
	global_load_dwordx4 v[58:61], v[58:59], off nt
	s_nop 0
	global_load_dwordx4 v[62:65], v[62:63], off nt
	v_add_co_u32_e32 v66, vcc, s80, v82
	v_readlane_b32 s49, v253, 27
	s_nop 0
	v_addc_co_u32_e32 v67, vcc, 0, v83, vcc
	v_add_co_u32_e32 v70, vcc, s81, v82
	v_readlane_b32 s50, v253, 28
	s_nop 0
	v_addc_co_u32_e32 v71, vcc, 0, v83, vcc
	global_load_dwordx4 v[66:69], v[66:67], off nt
	s_nop 0
	global_load_dwordx4 v[70:73], v[70:71], off nt
	v_add_co_u32_e32 v74, vcc, s82, v82
	v_readlane_b32 s51, v253, 29
	s_nop 0
	v_addc_co_u32_e32 v75, vcc, 0, v83, vcc
	v_add_co_u32_e32 v78, vcc, s83, v82
	v_readlane_b32 s54, v253, 32
	s_nop 0
	v_addc_co_u32_e32 v79, vcc, 0, v83, vcc
	global_load_dwordx4 v[74:77], v[74:75], off nt
	s_nop 0
	global_load_dwordx4 v[78:81], v[78:79], off nt
	v_add_co_u32_e32 v84, vcc, s84, v82
	v_readlane_b32 s55, v253, 33
	s_nop 0
	v_addc_co_u32_e32 v85, vcc, 0, v83, vcc
	v_add_co_u32_e32 v86, vcc, s30, v82
	s_nop 1
	v_addc_co_u32_e32 v87, vcc, 0, v83, vcc
	global_load_dwordx4 v[82:85], v[84:85], off nt
	s_nop 0
	global_load_dwordx4 v[86:89], v[86:87], off nt
	s_waitcnt vmcnt(14)
	v_cvt_pk_bf16_f32 v26, v26, v30
	v_add_u32_e32 v30, v95, v110
	ds_write_b32 v30, v26
	v_cvt_pk_bf16_f32 v26, v27, v31
	ds_write_b32 v30, v26 offset:128
	v_cvt_pk_bf16_f32 v26, v28, v32
	ds_write_b32 v30, v26 offset:256
	v_cvt_pk_bf16_f32 v26, v29, v33
	ds_write_b32 v30, v26 offset:384
	s_waitcnt vmcnt(12)
	v_cvt_pk_bf16_f32 v26, v34, v38
	v_add_u32_e32 v27, v111, v110
	ds_write_b32 v27, v26
	v_cvt_pk_bf16_f32 v26, v35, v39
	ds_write_b32 v27, v26 offset:128
	v_cvt_pk_bf16_f32 v26, v36, v40
	ds_write_b32 v27, v26 offset:256
	v_cvt_pk_bf16_f32 v26, v37, v41
	ds_write_b32 v27, v26 offset:384
	s_waitcnt vmcnt(10)
; #define LAS __attribute__((address_space(3)))
; __device__ __forceinline__ unsigned pk2(float lo, float hi) { unsigned r; asm volatile("v_cvt_pk_bf16_f32 %0, %1, %2" : "=v"(r) : "v"(lo), "v"(hi)); return r; }
; __device__ __forceinline__ void p0_transpose_item(const float* W, int K, int N, const float* gain, const float* gain2  , bf16_t* WT, LAS unsigned* scr, int item, int lane) {
;     ...
;     for (int j = 0; j < 8; ++j) {
;         float g0 = 1.f, g1 = 1.f; if (gain) { g0 = gain[k0 + 8 * j + 2 * kq]; g1 = gain[k0 + 8 * j + 2 * kq + 1]; }
; #pragma unroll
;         for (int i = 0; i < 4; ++i) scr[(4 * n4 + i) * 32 + (((j ^ (n4 & 7)) << 2) | kq)] = pk2(r0[j][i] * g0, r1[j][i] * g1);
;     }
;     asm volatile("s_waitcnt lgkmcnt(0)" ::: "memory");
; #pragma unroll
;     for (int it = 0; it < 8; ++it) {
;         const int n = (lane >> 3) + 8 * it, c = lane & 7;
;         const u32x4 v = *(const LAS u32x4*)(scr + n * 32 + ((c ^ ((n >> 2) & 7)) << 2));
;         *(u32x4*)(WT + (size_t)(n0 + n) * K + k0 + 8 * c) = v;
;     }
	v_cvt_pk_bf16_f32 v26, v42, v46
	v_add_u32_e32 v27, v112, v110
	ds_write_b32 v27, v26
	v_cvt_pk_bf16_f32 v26, v43, v47
	ds_write_b32 v27, v26 offset:128
	v_cvt_pk_bf16_f32 v26, v44, v48
	ds_write_b32 v27, v26 offset:256
	v_cvt_pk_bf16_f32 v26, v45, v49
	ds_write_b32 v27, v26 offset:384
	s_waitcnt vmcnt(8)
	v_cvt_pk_bf16_f32 v26, v50, v54
	v_add_u32_e32 v27, v113, v110
	ds_write_b32 v27, v26
	v_cvt_pk_bf16_f32 v26, v51, v55
	ds_write_b32 v27, v26 offset:128
	v_cvt_pk_bf16_f32 v26, v52, v56
	ds_write_b32 v27, v26 offset:256
	v_cvt_pk_bf16_f32 v26, v53, v57
	ds_write_b32 v27, v26 offset:384
	s_waitcnt vmcnt(6)
	v_cvt_pk_bf16_f32 v26, v58, v62
	v_add_u32_e32 v27, v114, v110
	ds_write_b32 v27, v26
	v_cvt_pk_bf16_f32 v26, v59, v63
	ds_write_b32 v27, v26 offset:128
	v_cvt_pk_bf16_f32 v26, v60, v64
	ds_write_b32 v27, v26 offset:256
	v_cvt_pk_bf16_f32 v26, v61, v65
	ds_write_b32 v27, v26 offset:384
	s_waitcnt vmcnt(4)
	v_cvt_pk_bf16_f32 v26, v66, v70
	v_add_u32_e32 v27, v115, v110
	ds_write_b32 v27, v26
	v_cvt_pk_bf16_f32 v26, v67, v71
	ds_write_b32 v27, v26 offset:128
	v_cvt_pk_bf16_f32 v26, v68, v72
	ds_write_b32 v27, v26 offset:256
	v_cvt_pk_bf16_f32 v26, v69, v73
	ds_write_b32 v27, v26 offset:384
	s_waitcnt vmcnt(2)
	v_cvt_pk_bf16_f32 v26, v74, v78
	v_add_u32_e32 v27, v116, v110
	ds_write_b32 v27, v26
	v_cvt_pk_bf16_f32 v26, v75, v79
	ds_write_b32 v27, v26 offset:128
	v_cvt_pk_bf16_f32 v26, v76, v80
	ds_write_b32 v27, v26 offset:256
	v_cvt_pk_bf16_f32 v26, v77, v81
	ds_write_b32 v27, v26 offset:384
	s_waitcnt vmcnt(0)
	v_cvt_pk_bf16_f32 v26, v82, v86
	v_add_u32_e32 v27, v117, v110
	ds_write_b32 v27, v26
	v_cvt_pk_bf16_f32 v26, v83, v87
	ds_write_b32 v27, v26 offset:128
	v_cvt_pk_bf16_f32 v26, v84, v88
	ds_write_b32 v27, v26 offset:256
	v_cvt_pk_bf16_f32 v26, v85, v89
	ds_write_b32 v27, v26 offset:384
	v_lshlrev_b32_e32 v26, 7, v100
	v_mov_b32_e32 v27, v93
	v_lshl_add_u64 v[26:27], v[98:99], 0, v[26:27]
	v_lshlrev_b32_e32 v28, 1, v94
	v_mov_b32_e32 v29, v93
	s_waitcnt lgkmcnt(0)
	v_lshl_add_u64 v[26:27], v[26:27], 0, v[28:29]
	v_lshl_add_u64 v[34:35], v[26:27], 0, s[22:23]
	ds_read_b128 v[26:29], v119
	v_or_b32_e32 v30, v101, v118
	v_lshlrev_b32_e32 v30, 14, v30
	v_mov_b32_e32 v31, v93
	v_lshl_add_u64 v[36:37], v[34:35], 0, v[30:31]
	ds_read_b128 v[30:33], v121
	s_waitcnt lgkmcnt(1)
	global_store_dwordx4 v[36:37], v[26:29], off sc0 sc1
	s_nop 1
	v_or_b32_e32 v26, v101, v120
	v_lshlrev_b32_e32 v26, 14, v26
	v_mov_b32_e32 v27, v93
	v_lshl_add_u64 v[26:27], v[34:35], 0, v[26:27]
	s_waitcnt lgkmcnt(0)
	global_store_dwordx4 v[26:27], v[30:33], off sc0 sc1
	ds_read_b128 v[26:29], v123
	s_nop 0
	v_or_b32_e32 v30, v101, v122
	v_lshlrev_b32_e32 v30, 14, v30
	v_mov_b32_e32 v31, v93
	v_lshl_add_u64 v[36:37], v[34:35], 0, v[30:31]
	ds_read_b128 v[30:33], v125
	s_waitcnt lgkmcnt(1)
	global_store_dwordx4 v[36:37], v[26:29], off sc0 sc1
	s_nop 1
	v_or_b32_e32 v26, v101, v124
	v_lshlrev_b32_e32 v26, 14, v26
	v_mov_b32_e32 v27, v93
	v_lshl_add_u64 v[26:27], v[34:35], 0, v[26:27]
	s_waitcnt lgkmcnt(0)
	global_store_dwordx4 v[26:27], v[30:33], off sc0 sc1
	ds_read_b128 v[26:29], v127
	s_nop 0
	v_or_b32_e32 v30, v101, v126
	v_lshlrev_b32_e32 v30, 14, v30
	v_mov_b32_e32 v31, v93
	v_lshl_add_u64 v[36:37], v[34:35], 0, v[30:31]
	ds_read_b128 v[30:33], v129
	s_waitcnt lgkmcnt(1)
	global_store_dwordx4 v[36:37], v[26:29], off sc0 sc1
	s_nop 1
	v_or_b32_e32 v26, v101, v128
	v_lshlrev_b32_e32 v26, 14, v26
	v_mov_b32_e32 v27, v93
	v_lshl_add_u64 v[26:27], v[34:35], 0, v[26:27]
	s_waitcnt lgkmcnt(0)
	global_store_dwordx4 v[26:27], v[30:33], off sc0 sc1
	ds_read_b128 v[26:29], v131
	s_nop 0
	v_or_b32_e32 v30, v101, v130
	v_lshlrev_b32_e32 v30, 14, v30
	v_mov_b32_e32 v31, v93
	v_lshl_add_u64 v[36:37], v[34:35], 0, v[30:31]
	ds_read_b128 v[30:33], v133
	s_waitcnt lgkmcnt(1)
	global_store_dwordx4 v[36:37], v[26:29], off sc0 sc1
	s_nop 1
	v_or_b32_e32 v26, v101, v132
	v_lshlrev_b32_e32 v26, 14, v26
	v_mov_b32_e32 v27, v93
	v_lshl_add_u64 v[26:27], v[34:35], 0, v[26:27]
	s_waitcnt lgkmcnt(0)
	global_store_dwordx4 v[26:27], v[30:33], off sc0 sc1
	s_waitcnt lgkmcnt(0)

; #define LAS __attribute__((address_space(3)))
; __device__ __forceinline__ unsigned pk2(float lo, float hi) { unsigned r; asm volatile("v_cvt_pk_bf16_f32 %0, %1, %2" : "=v"(r) : "v"(lo), "v"(hi)); return r; }
; __device__ __forceinline__ void p0_transpose_item(const float* W, int K, int N, const float* gain, const float* gain2  , bf16_t* WT, LAS unsigned* scr, int item, int lane) {
;     ...
;     for (int j = 0; j < 8; ++j) {
;         float g0 = 1.f, g1 = 1.f; if (gain) { g0 = gain[k0 + 8 * j + 2 * kq]; g1 = gain[k0 + 8 * j + 2 * kq + 1]; }
; #pragma unroll
;         for (int i = 0; i < 4; ++i) scr[(4 * n4 + i) * 32 + (((j ^ (n4 & 7)) << 2) | kq)] = pk2(r0[j][i] * g0, r1[j][i] * g1);
;     }
;     asm volatile("s_waitcnt lgkmcnt(0)" ::: "memory");
; #pragma unroll
;     for (int it = 0; it < 8; ++it) {
;         const int n = (lane >> 3) + 8 * it, c = lane & 7;
;         const u32x4 v = *(const LAS u32x4*)(scr + n * 32 + ((c ^ ((n >> 2) & 7)) << 2));
;         *(u32x4*)(WT + (size_t)(n0 + n) * K + k0 + 8 * c) = v;
;     }
.Lmy_w162:
	s_waitcnt vmcnt(0)
	v_mul_f32_e32 v26, v26, v42
	v_mul_f32_e32 v30, v30, v43
	v_cvt_pk_bf16_f32 v26, v26, v30
	v_add_u32_e32 v30, v117, v110
	ds_write_b32 v30, v26
	v_mul_f32_e32 v26, v27, v42
	v_mul_f32_e32 v27, v31, v43
	v_cvt_pk_bf16_f32 v26, v26, v27
	ds_write_b32 v30, v26 offset:128
	v_mul_f32_e32 v26, v28, v42
	v_mul_f32_e32 v27, v32, v43
	v_cvt_pk_bf16_f32 v26, v26, v27
	ds_write_b32 v30, v26 offset:256
	v_mul_f32_e32 v26, v29, v42
	v_mul_f32_e32 v27, v33, v43
	v_cvt_pk_bf16_f32 v26, v26, v27
	ds_write_b32 v30, v26 offset:384
	v_lshlrev_b32_e32 v26, 1, v109
	v_mov_b32_e32 v27, v93
	v_lshl_add_u64 v[26:27], v[98:99], 0, v[26:27]
	v_lshlrev_b32_e32 v28, 1, v94
	v_mov_b32_e32 v29, v93
	s_waitcnt lgkmcnt(0)
	v_lshl_add_u64 v[26:27], v[26:27], 0, v[28:29]
	v_lshl_add_u64 v[34:35], v[26:27], 0, s[24:25]
	ds_read_b128 v[26:29], v119
	v_or_b32_e32 v30, v108, v118
	v_lshlrev_b32_e32 v30, 12, v30
	v_mov_b32_e32 v31, v93
	v_lshl_add_u64 v[36:37], v[34:35], 0, v[30:31]
	ds_read_b128 v[30:33], v121
	s_waitcnt lgkmcnt(1)
	global_store_dwordx4 v[36:37], v[26:29], off sc0 sc1
	s_nop 1
	v_or_b32_e32 v26, v108, v120
	v_lshlrev_b32_e32 v26, 12, v26
	v_mov_b32_e32 v27, v93
	v_lshl_add_u64 v[26:27], v[34:35], 0, v[26:27]
	s_waitcnt lgkmcnt(0)
	global_store_dwordx4 v[26:27], v[30:33], off sc0 sc1
	ds_read_b128 v[26:29], v123
	s_nop 0
	v_or_b32_e32 v30, v108, v122
	v_lshlrev_b32_e32 v30, 12, v30
	v_mov_b32_e32 v31, v93
	v_lshl_add_u64 v[36:37], v[34:35], 0, v[30:31]
	ds_read_b128 v[30:33], v125
	s_waitcnt lgkmcnt(1)
	global_store_dwordx4 v[36:37], v[26:29], off sc0 sc1
	s_nop 1
	v_or_b32_e32 v26, v108, v124
	v_lshlrev_b32_e32 v26, 12, v26
	v_mov_b32_e32 v27, v93
	v_lshl_add_u64 v[26:27], v[34:35], 0, v[26:27]
	s_waitcnt lgkmcnt(0)
	global_store_dwordx4 v[26:27], v[30:33], off sc0 sc1
	ds_read_b128 v[26:29], v127
	s_nop 0
	v_or_b32_e32 v30, v108, v126
	v_lshlrev_b32_e32 v30, 12, v30
	v_mov_b32_e32 v31, v93
	v_lshl_add_u64 v[36:37], v[34:35], 0, v[30:31]
	ds_read_b128 v[30:33], v129
	s_waitcnt lgkmcnt(1)
	global_store_dwordx4 v[36:37], v[26:29], off sc0 sc1
	s_nop 1
	v_or_b32_e32 v26, v108, v128
	v_lshlrev_b32_e32 v26, 12, v26
	v_mov_b32_e32 v27, v93
	v_lshl_add_u64 v[26:27], v[34:35], 0, v[26:27]
	s_waitcnt lgkmcnt(0)
	global_store_dwordx4 v[26:27], v[30:33], off sc0 sc1
	ds_read_b128 v[26:29], v131
	s_nop 0
	v_or_b32_e32 v30, v108, v130
	v_lshlrev_b32_e32 v30, 12, v30
	v_mov_b32_e32 v31, v93
	v_lshl_add_u64 v[36:37], v[34:35], 0, v[30:31]
	ds_read_b128 v[30:33], v133
	s_waitcnt lgkmcnt(1)
	global_store_dwordx4 v[36:37], v[26:29], off sc0 sc1
	s_nop 1
	v_or_b32_e32 v26, v108, v132
	v_lshlrev_b32_e32 v26, 12, v26
	v_mov_b32_e32 v27, v93
	v_lshl_add_u64 v[26:27], v[34:35], 0, v[26:27]
	s_waitcnt lgkmcnt(0)
	global_store_dwordx4 v[26:27], v[30:33], off sc0 sc1
	s_waitcnt lgkmcnt(0)
